# attention loops: x+0 row-sum seeds and max(x,x) canonicalisations feeding another max removed
# baseline (speedup 1.0000x reference)
.LBB0_684:
	v_pk_fma_f32 v[2:3], v[80:81], s[8:9], v[198:199] op_sel_hi:[1,0,0] neg_lo:[0,0,1] neg_hi:[0,0,1]
	v_lshl_add_u32 v0, s38, 6, v211
	v_exp_f32_e32 v14, v2
	v_exp_f32_e32 v15, v3
	v_pk_fma_f32 v[2:3], v[82:83], s[8:9], v[198:199] op_sel_hi:[1,0,0] neg_lo:[0,0,1] neg_hi:[0,0,1]
	v_pk_fma_f32 v[6:7], v[86:87], s[8:9], v[198:199] op_sel_hi:[1,0,0] neg_lo:[0,0,1] neg_hi:[0,0,1]
	v_exp_f32_e32 v216, v2
	v_exp_f32_e32 v217, v3
	v_pk_fma_f32 v[2:3], v[84:85], s[8:9], v[198:199] op_sel_hi:[1,0,0] neg_lo:[0,0,1] neg_hi:[0,0,1]
	v_exp_f32_e32 v220, v6
	v_exp_f32_e32 v218, v2
	v_exp_f32_e32 v219, v3
	ds_read_b128 v[2:5], v0 offset:25600
	ds_read_b128 v[10:13], v0 offset:25632
	v_exp_f32_e32 v221, v7
	v_cvt_pk_bf16_f32 v6, v14, v15
	v_cvt_pk_bf16_f32 v7, v216, v217
	v_cvt_pk_bf16_f32 v8, v218, v219
	v_cvt_pk_bf16_f32 v9, v220, v221
	v_pk_fma_f32 v[84:85], v[88:89], s[8:9], v[198:199] op_sel_hi:[1,0,0] neg_lo:[0,0,1] neg_hi:[0,0,1]
	s_xor_b64 s[40:41], s[28:29], -1
	s_waitcnt lgkmcnt(1)
	v_mfma_f32_32x32x16_bf16 v[64:79], v[2:5], v[6:9], v[64:79]
	ds_read_b128 v[2:5], v0 offset:30208
	ds_read_b128 v[80:83], v0 offset:30240
	v_exp_f32_e32 v88, v84
	v_exp_f32_e32 v89, v85
	s_mov_b32 s38, 1
	s_mov_b64 s[28:29], 0
	s_and_b64 vcc, exec, s[40:41]
	s_waitcnt lgkmcnt(1)
	v_mfma_f32_32x32x16_bf16 v[48:63], v[2:5], v[6:9], v[48:63]
	ds_read_b128 v[2:5], v0 offset:34816
	ds_read_b128 v[84:87], v0 offset:39424
	ds_read_b128 v[212:215], v0 offset:34848
	s_waitcnt lgkmcnt(2)
	v_mfma_f32_32x32x16_bf16 v[32:47], v[2:5], v[6:9], v[32:47]
	v_fma_f32 v2, v90, s8, -v198
	v_fma_f32 v3, v91, s8, -v198
	v_exp_f32_e32 v90, v2
	v_exp_f32_e32 v91, v3
	v_pk_fma_f32 v[2:3], v[92:93], s[8:9], v[198:199] op_sel_hi:[1,0,0] neg_lo:[0,0,1] neg_hi:[0,0,1]
	s_nop 0
	v_exp_f32_e32 v92, v2
	v_exp_f32_e32 v93, v3
	ds_read_b128 v[2:5], v0 offset:39456
	s_waitcnt lgkmcnt(2)
	v_mfma_f32_32x32x16_bf16 v[16:31], v[84:87], v[6:9], v[16:31]
	v_fma_f32 v6, v94, s8, -v198
	v_fma_f32 v7, v95, s8, -v198
	v_cvt_pk_bf16_f32 v8, v92, v93
	v_exp_f32_e32 v84, v6
	v_exp_f32_e32 v85, v7
	v_cvt_pk_bf16_f32 v6, v88, v89
	v_cvt_pk_bf16_f32 v7, v90, v91
	v_cvt_pk_bf16_f32 v9, v84, v85
	s_nop 1
	v_mfma_f32_32x32x16_bf16 v[64:79], v[10:13], v[6:9], v[64:79]
	v_add_f32_e64 v10, v216, v14
	v_add_f32_e64 v11, v217, v15
	v_add_f32_e64 v10, v218, v10
	v_add_f32_e64 v11, v219, v11
	v_pk_add_f32 v[10:11], v[220:221], v[10:11]
	v_mfma_f32_32x32x16_bf16 v[48:63], v[80:83], v[6:9], v[48:63]
	v_add_f32_e64 v10, v88, v10
	v_add_f32_e64 v11, v89, v11
	v_add_f32_e64 v10, v90, v10
	v_add_f32_e64 v11, v91, v11
	v_add_f32_e64 v10, v92, v10
	v_add_f32_e64 v11, v93, v11
	v_pk_add_f32 v[10:11], v[84:85], v[10:11]
	s_waitcnt lgkmcnt(1)
	v_mfma_f32_32x32x16_bf16 v[32:47], v[212:215], v[6:9], v[32:47]
	v_add_f32_e32 v0, v10, v11
	v_add_f32_e32 v193, v193, v0
	s_waitcnt lgkmcnt(0)
	v_mfma_f32_32x32x16_bf16 v[16:31], v[2:5], v[6:9], v[16:31]
	s_cbranch_vccnz .LBB0_680
.LBB0_685:
	v_lshl_or_b32 v0, s38, 5, v202
	v_mad_u32_u24 v0, v0, s30, v208
	ds_read_b128 v[2:5], v0
	ds_read_b128 v[6:9], v0 offset:32
	s_waitcnt lgkmcnt(1)
	v_mfma_f32_32x32x16_bf16 v[80:95], v[2:5], v[148:151], 0
	s_waitcnt lgkmcnt(0)
	v_mfma_f32_32x32x16_bf16 v[80:95], v[6:9], v[96:99], v[80:95]
	ds_read_b128 v[2:5], v0 offset:64
	ds_read_b128 v[6:9], v0 offset:96
	s_waitcnt lgkmcnt(1)
	v_mfma_f32_32x32x16_bf16 v[80:95], v[2:5], v[100:103], v[80:95]
	s_waitcnt lgkmcnt(0)
	v_mfma_f32_32x32x16_bf16 v[80:95], v[6:9], v[104:107], v[80:95]
	ds_read_b128 v[2:5], v0 offset:128
	ds_read_b128 v[6:9], v0 offset:160
	s_waitcnt lgkmcnt(1)
	v_mfma_f32_32x32x16_bf16 v[80:95], v[2:5], v[108:111], v[80:95]
	s_waitcnt lgkmcnt(0)
	v_mfma_f32_32x32x16_bf16 v[80:95], v[6:9], v[112:115], v[80:95]
	ds_read_b128 v[2:5], v0 offset:192
	ds_read_b128 v[6:9], v0 offset:224
	s_waitcnt lgkmcnt(1)
	v_mfma_f32_32x32x16_bf16 v[80:95], v[2:5], v[116:119], v[80:95]
	s_waitcnt lgkmcnt(0)
	v_mfma_f32_32x32x16_bf16 v[80:95], v[6:9], v[120:123], v[80:95]
	ds_read_b128 v[2:5], v0 offset:256
	ds_read_b128 v[6:9], v0 offset:288
	s_waitcnt lgkmcnt(1)
	v_mfma_f32_32x32x16_bf16 v[80:95], v[2:5], v[124:127], v[80:95]
	s_waitcnt lgkmcnt(0)
	v_mfma_f32_32x32x16_bf16 v[80:95], v[6:9], v[128:131], v[80:95]
	ds_read_b128 v[2:5], v0 offset:320
	ds_read_b128 v[6:9], v0 offset:352
	s_waitcnt lgkmcnt(1)
	v_mfma_f32_32x32x16_bf16 v[80:95], v[2:5], v[132:135], v[80:95]
	s_waitcnt lgkmcnt(0)
	v_mfma_f32_32x32x16_bf16 v[80:95], v[6:9], v[140:143], v[80:95]
	s_nop 11
	v_max_f32_e32 v0, v80, v81
	v_max3_f32 v0, v0, v82, v83
	v_max3_f32 v0, v0, v84, v85
	v_max3_f32 v0, v0, v86, v87
	v_max3_f32 v0, v0, v88, v89
	v_max3_f32 v0, v0, v90, v91
	v_max3_f32 v0, v0, v92, v93
	v_max3_f32 v0, v0, v94, v95
	v_mov_b32_e32 v2, v0
	s_nop 1
	v_permlane32_swap_b32_e32 v2, v0
	s_waitcnt lgkmcnt(0)
	v_max_f32_e32 v0, v0, v2
	v_mul_f32_e32 v0, 0x3dd53b94, v0
	v_add_f32_e32 v250, 0xc1000000, v0
	v_cmp_gt_f32_e32 vcc, v250, v198
	s_cbranch_vccz .LBB0_684
	v_max_f32_e32 v0, v0, v0
	v_max_f32_e32 v2, v198, v198
	v_max_f32_e32 v2, v2, v0
	v_sub_f32_e32 v0, v198, v2
	v_exp_f32_e32 v0, v0
	v_mov_b32_e32 v198, v2
	v_pk_mul_f32 v[78:79], v[78:79], v[0:1] op_sel_hi:[1,0]
	v_pk_mul_f32 v[76:77], v[76:77], v[0:1] op_sel_hi:[1,0]
	v_pk_mul_f32 v[74:75], v[74:75], v[0:1] op_sel_hi:[1,0]
	v_pk_mul_f32 v[72:73], v[72:73], v[0:1] op_sel_hi:[1,0]
	v_pk_mul_f32 v[70:71], v[70:71], v[0:1] op_sel_hi:[1,0]
	v_pk_mul_f32 v[68:69], v[68:69], v[0:1] op_sel_hi:[1,0]
	v_pk_mul_f32 v[66:67], v[66:67], v[0:1] op_sel_hi:[1,0]
	v_pk_mul_f32 v[64:65], v[64:65], v[0:1] op_sel_hi:[1,0]
	v_pk_mul_f32 v[62:63], v[62:63], v[0:1] op_sel_hi:[1,0]
	v_pk_mul_f32 v[60:61], v[60:61], v[0:1] op_sel_hi:[1,0]
	v_pk_mul_f32 v[58:59], v[58:59], v[0:1] op_sel_hi:[1,0]
	v_pk_mul_f32 v[56:57], v[56:57], v[0:1] op_sel_hi:[1,0]
	v_pk_mul_f32 v[54:55], v[54:55], v[0:1] op_sel_hi:[1,0]
	v_pk_mul_f32 v[52:53], v[52:53], v[0:1] op_sel_hi:[1,0]
	v_pk_mul_f32 v[50:51], v[50:51], v[0:1] op_sel_hi:[1,0]
	v_pk_mul_f32 v[48:49], v[48:49], v[0:1] op_sel_hi:[1,0]
	v_pk_mul_f32 v[46:47], v[46:47], v[0:1] op_sel_hi:[1,0]
	v_pk_mul_f32 v[44:45], v[44:45], v[0:1] op_sel_hi:[1,0]
	v_pk_mul_f32 v[42:43], v[42:43], v[0:1] op_sel_hi:[1,0]
	v_pk_mul_f32 v[40:41], v[40:41], v[0:1] op_sel_hi:[1,0]
	v_pk_mul_f32 v[38:39], v[38:39], v[0:1] op_sel_hi:[1,0]
	v_pk_mul_f32 v[36:37], v[36:37], v[0:1] op_sel_hi:[1,0]
	v_pk_mul_f32 v[34:35], v[34:35], v[0:1] op_sel_hi:[1,0]
	v_pk_mul_f32 v[32:33], v[32:33], v[0:1] op_sel_hi:[1,0]
	v_pk_mul_f32 v[30:31], v[30:31], v[0:1] op_sel_hi:[1,0]
	v_pk_mul_f32 v[28:29], v[28:29], v[0:1] op_sel_hi:[1,0]
	v_pk_mul_f32 v[26:27], v[26:27], v[0:1] op_sel_hi:[1,0]
	v_pk_mul_f32 v[24:25], v[24:25], v[0:1] op_sel_hi:[1,0]
	v_pk_mul_f32 v[22:23], v[22:23], v[0:1] op_sel_hi:[1,0]
	v_pk_mul_f32 v[20:21], v[20:21], v[0:1] op_sel_hi:[1,0]
	v_pk_mul_f32 v[18:19], v[18:19], v[0:1] op_sel_hi:[1,0]
	v_pk_mul_f32 v[16:17], v[16:17], v[0:1] op_sel_hi:[1,0]
	v_mul_f32_e32 v193, v193, v0
	s_branch .LBB0_684

.LBB0_1019:
	v_mov_b32_e32 v3, v180
	v_pk_fma_f32 v[4:5], v[80:81], s[18:19], v[2:3] op_sel_hi:[1,0,1] neg_lo:[0,0,1] neg_hi:[0,0,1]
	v_pk_fma_f32 v[8:9], v[86:87], s[18:19], v[2:3] op_sel_hi:[1,0,1] neg_lo:[0,0,1] neg_hi:[0,0,1]
	v_exp_f32_e32 v196, v4
	v_exp_f32_e32 v197, v5
	v_pk_fma_f32 v[4:5], v[82:83], s[18:19], v[2:3] op_sel_hi:[1,0,1] neg_lo:[0,0,1] neg_hi:[0,0,1]
	v_exp_f32_e32 v210, v8
	v_exp_f32_e32 v206, v4
	v_exp_f32_e32 v207, v5
	v_pk_fma_f32 v[4:5], v[84:85], s[18:19], v[2:3] op_sel_hi:[1,0,1] neg_lo:[0,0,1] neg_hi:[0,0,1]
	v_exp_f32_e32 v211, v9
	v_exp_f32_e32 v208, v4
	v_exp_f32_e32 v209, v5
	ds_read_b128 v[4:7], v194 offset:9280
	ds_read_b128 v[12:15], v194 offset:9312
	v_cvt_pk_bf16_f32 v8, v196, v197
	v_cvt_pk_bf16_f32 v9, v206, v207
	v_cvt_pk_bf16_f32 v10, v208, v209
	v_cvt_pk_bf16_f32 v11, v210, v211
	v_pk_fma_f32 v[84:85], v[88:89], s[18:19], v[2:3] op_sel_hi:[1,0,1] neg_lo:[0,0,1] neg_hi:[0,0,1]
	v_lshl_add_u64 v[178:179], v[178:179], 0, s[20:21]
	s_waitcnt lgkmcnt(1)
	v_mfma_f32_32x32x16_bf16 v[64:79], v[4:7], v[8:11], v[64:79]
	ds_read_b128 v[4:7], v194 offset:13888
	ds_read_b128 v[80:83], v194 offset:13920
	v_exp_f32_e32 v88, v84
	v_exp_f32_e32 v89, v85
	v_lshl_add_u64 v[176:177], v[176:177], 0, s[20:21]
	v_lshl_add_u64 v[174:175], v[174:175], 0, s[20:21]
	v_lshl_add_u64 v[172:173], v[172:173], 0, s[20:21]
	s_cmp_eq_u32 s31, s0
	s_waitcnt lgkmcnt(1)
	v_mfma_f32_32x32x16_bf16 v[48:63], v[4:7], v[8:11], v[48:63]
	ds_read_b128 v[4:7], v194 offset:18496
	ds_read_b128 v[84:87], v194 offset:23104
	ds_read_b128 v[202:205], v194 offset:18528
	v_lshl_add_u64 v[170:171], v[170:171], 0, s[22:23]
	s_waitcnt lgkmcnt(2)
	v_mfma_f32_32x32x16_bf16 v[32:47], v[4:7], v[8:11], v[32:47]
	v_fma_f32 v4, v90, s18, -v2
	v_fma_f32 v5, v91, s18, -v3
	v_exp_f32_e32 v90, v4
	v_exp_f32_e32 v91, v5
	v_pk_fma_f32 v[4:5], v[92:93], s[18:19], v[2:3] op_sel_hi:[1,0,1] neg_lo:[0,0,1] neg_hi:[0,0,1]
	v_pk_fma_f32 v[2:3], v[94:95], s[18:19], v[2:3] op_sel_hi:[1,0,1] neg_lo:[0,0,1] neg_hi:[0,0,1]
	v_exp_f32_e32 v92, v4
	v_exp_f32_e32 v93, v5
	ds_read_b128 v[4:7], v194 offset:23136
	s_waitcnt lgkmcnt(2)
	v_mfma_f32_32x32x16_bf16 v[16:31], v[84:87], v[8:11], v[16:31]
	v_exp_f32_e32 v2, v2
	v_exp_f32_e32 v3, v3
	v_cvt_pk_bf16_f32 v8, v88, v89
	v_cvt_pk_bf16_f32 v9, v90, v91
	v_cvt_pk_bf16_f32 v10, v92, v93
	v_cvt_pk_bf16_f32 v11, v2, v3
	s_nop 1
	v_mfma_f32_32x32x16_bf16 v[64:79], v[12:15], v[8:11], v[64:79]
	v_add_f32_e64 v12, v206, v196
	v_add_f32_e64 v13, v207, v197
	v_add_f32_e64 v12, v208, v12
	v_add_f32_e64 v13, v209, v13
	v_pk_add_f32 v[12:13], v[210:211], v[12:13]
	v_mfma_f32_32x32x16_bf16 v[48:63], v[80:83], v[8:11], v[48:63]
	v_add_f32_e64 v12, v88, v12
	v_add_f32_e64 v13, v89, v13
	v_add_f32_e64 v12, v90, v12
	v_add_f32_e64 v13, v91, v13
	v_add_f32_e64 v12, v92, v12
	v_add_f32_e64 v13, v93, v13
	v_pk_add_f32 v[2:3], v[2:3], v[12:13]
	s_waitcnt lgkmcnt(1)
	v_mfma_f32_32x32x16_bf16 v[32:47], v[202:205], v[8:11], v[32:47]
	v_add_f32_e32 v2, v2, v3
	v_add_f32_e32 v196, v1, v2
	s_waitcnt lgkmcnt(0)
	v_mfma_f32_32x32x16_bf16 v[16:31], v[4:7], v[8:11], v[16:31]
	s_cbranch_scc1 .LBB0_1026

.LBB0_1022:
	ds_read_b128 v[2:5], v193
	ds_read_b128 v[6:9], v193 offset:32
	s_waitcnt lgkmcnt(1)
	v_mfma_f32_32x32x16_bf16 v[80:95], v[2:5], v[96:99], 0
	s_waitcnt lgkmcnt(0)
	v_mfma_f32_32x32x16_bf16 v[80:95], v[6:9], v[100:103], v[80:95]
	ds_read_b128 v[2:5], v193 offset:64
	ds_read_b128 v[6:9], v193 offset:96
	s_waitcnt lgkmcnt(1)
	v_mfma_f32_32x32x16_bf16 v[80:95], v[2:5], v[104:107], v[80:95]
	s_waitcnt lgkmcnt(0)
	v_mfma_f32_32x32x16_bf16 v[80:95], v[6:9], v[108:111], v[80:95]
	s_nop 11
	v_max_f32_e32 v1, v80, v81
	v_max3_f32 v1, v1, v82, v83
	v_max3_f32 v1, v1, v84, v85
	v_max3_f32 v1, v1, v86, v87
	v_max3_f32 v1, v1, v88, v89
	v_max3_f32 v1, v1, v90, v91
	v_max3_f32 v1, v1, v92, v93
	v_max3_f32 v1, v1, v94, v95
	v_mov_b32_e32 v2, v1
	s_nop 1
	v_permlane32_swap_b32_e32 v2, v1
	s_waitcnt lgkmcnt(0)
	v_max_f32_e32 v1, v1, v2
	v_mul_f32_e32 v1, 0x3e38aa3b, v1
	v_add_f32_e32 v250, 0xc1000000, v1
	v_cmp_gt_f32_e32 vcc, v250, v180
	s_cbranch_vccz .LBB0_1024
	v_max_f32_e32 v1, v1, v1
	v_max_f32_e32 v2, v180, v180
	v_max_f32_e32 v1, v2, v1
	v_sub_f32_e32 v2, v180, v1
	v_exp_f32_e32 v2, v2
	v_mov_b32_e32 v180, v1
	v_pk_mul_f32 v[78:79], v[78:79], v[2:3] op_sel_hi:[1,0]
	v_pk_mul_f32 v[76:77], v[76:77], v[2:3] op_sel_hi:[1,0]
	v_pk_mul_f32 v[74:75], v[74:75], v[2:3] op_sel_hi:[1,0]
	v_pk_mul_f32 v[72:73], v[72:73], v[2:3] op_sel_hi:[1,0]
	v_pk_mul_f32 v[70:71], v[70:71], v[2:3] op_sel_hi:[1,0]
	v_pk_mul_f32 v[68:69], v[68:69], v[2:3] op_sel_hi:[1,0]
	v_pk_mul_f32 v[66:67], v[66:67], v[2:3] op_sel_hi:[1,0]
	v_pk_mul_f32 v[64:65], v[64:65], v[2:3] op_sel_hi:[1,0]
	v_pk_mul_f32 v[62:63], v[62:63], v[2:3] op_sel_hi:[1,0]
	v_pk_mul_f32 v[60:61], v[60:61], v[2:3] op_sel_hi:[1,0]
	v_pk_mul_f32 v[58:59], v[58:59], v[2:3] op_sel_hi:[1,0]
	v_pk_mul_f32 v[56:57], v[56:57], v[2:3] op_sel_hi:[1,0]
	v_pk_mul_f32 v[54:55], v[54:55], v[2:3] op_sel_hi:[1,0]
	v_pk_mul_f32 v[52:53], v[52:53], v[2:3] op_sel_hi:[1,0]
	v_pk_mul_f32 v[50:51], v[50:51], v[2:3] op_sel_hi:[1,0]
	v_pk_mul_f32 v[48:49], v[48:49], v[2:3] op_sel_hi:[1,0]
	v_pk_mul_f32 v[46:47], v[46:47], v[2:3] op_sel_hi:[1,0]
	v_pk_mul_f32 v[44:45], v[44:45], v[2:3] op_sel_hi:[1,0]
	v_pk_mul_f32 v[42:43], v[42:43], v[2:3] op_sel_hi:[1,0]
	v_pk_mul_f32 v[40:41], v[40:41], v[2:3] op_sel_hi:[1,0]
	v_pk_mul_f32 v[38:39], v[38:39], v[2:3] op_sel_hi:[1,0]
	v_pk_mul_f32 v[36:37], v[36:37], v[2:3] op_sel_hi:[1,0]
	v_pk_mul_f32 v[34:35], v[34:35], v[2:3] op_sel_hi:[1,0]
	v_pk_mul_f32 v[32:33], v[32:33], v[2:3] op_sel_hi:[1,0]
	v_pk_mul_f32 v[30:31], v[30:31], v[2:3] op_sel_hi:[1,0]
	v_pk_mul_f32 v[28:29], v[28:29], v[2:3] op_sel_hi:[1,0]
	v_pk_mul_f32 v[26:27], v[26:27], v[2:3] op_sel_hi:[1,0]
	v_pk_mul_f32 v[24:25], v[24:25], v[2:3] op_sel_hi:[1,0]
	v_pk_mul_f32 v[22:23], v[22:23], v[2:3] op_sel_hi:[1,0]
	v_pk_mul_f32 v[20:21], v[20:21], v[2:3] op_sel_hi:[1,0]
	v_pk_mul_f32 v[18:19], v[18:19], v[2:3] op_sel_hi:[1,0]
	v_pk_mul_f32 v[16:17], v[16:17], v[2:3] op_sel_hi:[1,0]
	v_mul_f32_e32 v196, v196, v2
.LBB0_1024:
	v_pk_fma_f32 v[2:3], v[80:81], s[18:19], v[180:181] op_sel_hi:[1,0,0] neg_lo:[0,0,1] neg_hi:[0,0,1]
	v_pk_fma_f32 v[6:7], v[86:87], s[18:19], v[180:181] op_sel_hi:[1,0,0] neg_lo:[0,0,1] neg_hi:[0,0,1]
	v_exp_f32_e32 v214, v2
	v_exp_f32_e32 v215, v3
	v_pk_fma_f32 v[2:3], v[82:83], s[18:19], v[180:181] op_sel_hi:[1,0,0] neg_lo:[0,0,1] neg_hi:[0,0,1]
	v_exp_f32_e32 v220, v6
	v_exp_f32_e32 v216, v2
	v_exp_f32_e32 v217, v3
	v_pk_fma_f32 v[2:3], v[84:85], s[18:19], v[180:181] op_sel_hi:[1,0,0] neg_lo:[0,0,1] neg_hi:[0,0,1]
	v_exp_f32_e32 v221, v7
	v_exp_f32_e32 v218, v2
	v_exp_f32_e32 v219, v3
	ds_read_b128 v[2:5], v194 offset:9216
	ds_read_b128 v[10:13], v194 offset:9248
	v_cvt_pk_bf16_f32 v6, v214, v215
	v_cvt_pk_bf16_f32 v7, v216, v217
	v_cvt_pk_bf16_f32 v8, v218, v219
	v_cvt_pk_bf16_f32 v9, v220, v221
	v_pk_fma_f32 v[14:15], v[88:89], s[18:19], v[180:181] op_sel_hi:[1,0,0] neg_lo:[0,0,1] neg_hi:[0,0,1]
	s_waitcnt lgkmcnt(1)
	v_mfma_f32_32x32x16_bf16 v[64:79], v[2:5], v[6:9], v[64:79]
	ds_read_b128 v[2:5], v194 offset:13824
	ds_read_b128 v[202:205], v194 offset:13856
	v_exp_f32_e32 v222, v14
	v_exp_f32_e32 v223, v15
	s_waitcnt lgkmcnt(1)
	v_mfma_f32_32x32x16_bf16 v[48:63], v[2:5], v[6:9], v[48:63]
	ds_read_b128 v[2:5], v194 offset:18432
	ds_read_b128 v[80:83], v194 offset:23040
	ds_read_b128 v[206:209], v194 offset:18464
	ds_read_b128 v[210:213], v194 offset:23072
	s_waitcnt lgkmcnt(3)
	v_mfma_f32_32x32x16_bf16 v[32:47], v[2:5], v[6:9], v[32:47]
	v_fma_f32 v4, v92, s18, -v180
	v_fma_f32 v5, v93, s18, -v180
	v_fma_f32 v2, v90, s18, -v180
	v_fma_f32 v3, v91, s18, -v180
	v_exp_f32_e32 v224, v4
	v_exp_f32_e32 v225, v5
	v_pk_fma_f32 v[4:5], v[94:95], s[18:19], v[180:181] op_sel_hi:[1,0,0] neg_lo:[0,0,1] neg_hi:[0,0,1]
	v_exp_f32_e32 v2, v2
	v_exp_f32_e32 v3, v3
	v_exp_f32_e32 v226, v4
	v_exp_f32_e32 v227, v5
	s_waitcnt lgkmcnt(2)
	v_mfma_f32_32x32x16_bf16 v[16:31], v[80:83], v[6:9], v[16:31]
	v_cvt_pk_bf16_f32 v4, v222, v223
	v_cvt_pk_bf16_f32 v5, v2, v3
	v_cvt_pk_bf16_f32 v6, v224, v225
	v_cvt_pk_bf16_f32 v7, v226, v227
	s_nop 1
	v_mfma_f32_32x32x16_bf16 v[64:79], v[10:13], v[4:7], v[64:79]
	ds_read_b128 v[8:11], v193 offset:4608
	ds_read_b128 v[12:15], v193 offset:4640
	s_waitcnt lgkmcnt(1)
	v_mfma_f32_32x32x16_bf16 v[80:95], v[8:11], v[96:99], 0
	s_waitcnt lgkmcnt(0)
	v_mfma_f32_32x32x16_bf16 v[80:95], v[12:15], v[100:103], v[80:95]
	ds_read_b128 v[8:11], v193 offset:4672
	ds_read_b128 v[12:15], v193 offset:4704
	s_waitcnt lgkmcnt(1)
	v_mfma_f32_32x32x16_bf16 v[80:95], v[8:11], v[104:107], v[80:95]
	v_add_f32_e64 v8, v216, v214
	v_add_f32_e64 v9, v217, v215
	v_add_f32_e64 v8, v218, v8
	v_add_f32_e64 v9, v219, v9
	v_pk_add_f32 v[8:9], v[220:221], v[8:9]
	s_waitcnt lgkmcnt(0)
	v_mfma_f32_32x32x16_bf16 v[80:95], v[12:15], v[108:111], v[80:95]
	v_add_f32_e64 v8, v222, v8
	v_add_f32_e64 v9, v223, v9
	v_add_f32_e64 v2, v2, v8
	v_add_f32_e64 v3, v3, v9
	v_add_f32_e64 v2, v224, v2
	v_add_f32_e64 v3, v225, v3
	s_nop 5
	v_max_f32_e32 v1, v80, v81
	v_max3_f32 v1, v1, v82, v83
	v_max3_f32 v1, v1, v84, v85
	v_max3_f32 v1, v1, v86, v87
	v_max3_f32 v1, v1, v88, v89
	v_max3_f32 v1, v1, v90, v91
	v_max3_f32 v1, v1, v92, v93
	v_max3_f32 v8, v1, v94, v95
	ds_bpermute_b32 v9, v184, v8
	v_mfma_f32_32x32x16_bf16 v[48:63], v[202:205], v[4:7], v[48:63]
	v_add_f32_e64 v2, v226, v2
	v_add_f32_e64 v3, v227, v3
	v_add_f32_e32 v1, v2, v3
	s_waitcnt lgkmcnt(0)
	v_max_f32_e32 v2, v9, v9
	v_max_f32_e32 v2, v8, v2
	v_mul_f32_e32 v2, 0x3e38aa3b, v2
	v_add_f32_e32 v1, v196, v1
	v_mfma_f32_32x32x16_bf16 v[32:47], v[206:209], v[4:7], v[32:47]
	v_add_f32_e32 v250, 0xc1000000, v2
	v_cmp_gt_f32_e32 vcc, v250, v180
	v_mfma_f32_32x32x16_bf16 v[16:31], v[210:213], v[4:7], v[16:31]
	s_cbranch_vccnz .LBB0_1018
	v_mov_b64_e32 v[2:3], v[180:181]
	s_branch .LBB0_1019

.LBB0_1285:
	v_pk_fma_f32 v[64:65], v[64:65], s[18:19], v[152:153] op_sel_hi:[1,0,1] neg_lo:[0,0,1] neg_hi:[0,0,1]
	v_pk_fma_f32 v[72:73], v[72:73], s[18:19], v[152:153] op_sel_hi:[1,0,1] neg_lo:[0,0,1] neg_hi:[0,0,1]
	v_exp_f32_e32 v98, v64
	v_exp_f32_e32 v99, v65
	v_pk_fma_f32 v[64:65], v[66:67], s[18:19], v[152:153] op_sel_hi:[1,0,1] neg_lo:[0,0,1] neg_hi:[0,0,1]
	ds_read_b128 v[82:85], v171 offset:17504
	v_exp_f32_e32 v100, v64
	v_exp_f32_e32 v101, v65
	v_pk_fma_f32 v[64:65], v[68:69], s[18:19], v[152:153] op_sel_hi:[1,0,1] neg_lo:[0,0,1] neg_hi:[0,0,1]
	v_pk_fma_f32 v[68:69], v[70:71], s[18:19], v[152:153] op_sel_hi:[1,0,1] neg_lo:[0,0,1] neg_hi:[0,0,1]
	v_exp_f32_e32 v102, v64
	v_exp_f32_e32 v103, v65
	ds_read_b128 v[64:67], v171 offset:17472
	v_exp_f32_e32 v104, v68
	v_exp_f32_e32 v105, v69
	v_cvt_pk_bf16_f32 v68, v98, v99
	v_cvt_pk_bf16_f32 v69, v100, v101
	v_cvt_pk_bf16_f32 v70, v102, v103
	v_cvt_pk_bf16_f32 v71, v104, v105
	v_exp_f32_e32 v72, v72
	v_exp_f32_e32 v73, v73
	s_waitcnt lgkmcnt(0)
	v_mfma_f32_32x32x16_bf16 v[48:63], v[64:67], v[68:71], v[48:63]
	ds_read_b128 v[64:67], v171 offset:22080
	ds_read_b128 v[86:89], v171 offset:22112
	s_lshl_b32 s8, s24, 1
	s_add_i32 s41, s41, s33
	s_cmpk_gt_i32 s41, 0x3ff
	s_waitcnt lgkmcnt(1)
	v_mfma_f32_32x32x16_bf16 v[32:47], v[64:67], v[68:71], v[32:47]
	ds_read_b128 v[64:67], v171 offset:26688
	ds_read_b128 v[90:93], v171 offset:31296
	ds_read_b128 v[94:97], v171 offset:26720
	s_waitcnt lgkmcnt(2)
	v_mfma_f32_32x32x16_bf16 v[16:31], v[64:67], v[68:71], v[16:31]
	v_fma_f32 v64, v74, s18, -v152
	v_fma_f32 v65, v75, s18, -v153
	v_exp_f32_e32 v74, v64
	v_exp_f32_e32 v75, v65
	v_pk_fma_f32 v[64:65], v[76:77], s[18:19], v[152:153] op_sel_hi:[1,0,1] neg_lo:[0,0,1] neg_hi:[0,0,1]
	s_nop 0
	v_exp_f32_e32 v76, v64
	s_waitcnt lgkmcnt(1)
	v_mfma_f32_32x32x16_bf16 v[0:15], v[90:93], v[68:71], v[0:15]
	v_fma_f32 v68, v78, s18, -v152
	v_fma_f32 v69, v79, s18, -v153
	v_exp_f32_e32 v77, v65
	v_exp_f32_e32 v78, v68
	v_exp_f32_e32 v79, v69
	v_cvt_pk_bf16_f32 v68, v72, v73
	v_cvt_pk_bf16_f32 v69, v74, v75
	v_cvt_pk_bf16_f32 v70, v76, v77
	v_cvt_pk_bf16_f32 v71, v78, v79
	ds_read_b128 v[64:67], v171 offset:31328
	s_nop 0
	v_mfma_f32_32x32x16_bf16 v[48:63], v[82:85], v[68:71], v[48:63]
	v_add_f32_e64 v82, v100, v98
	v_add_f32_e64 v83, v101, v99
	v_add_f32_e64 v82, v102, v82
	v_add_f32_e64 v83, v103, v83
	v_pk_add_f32 v[82:83], v[104:105], v[82:83]
	v_mfma_f32_32x32x16_bf16 v[32:47], v[86:89], v[68:71], v[32:47]
	v_add_f32_e64 v72, v72, v82
	v_add_f32_e64 v73, v73, v83
	v_add_f32_e64 v72, v74, v72
	v_add_f32_e64 v73, v75, v73
	v_add_f32_e64 v72, v76, v72
	v_add_f32_e64 v73, v77, v73
	v_pk_add_f32 v[72:73], v[78:79], v[72:73]
	s_waitcnt lgkmcnt(1)
	v_mfma_f32_32x32x16_bf16 v[16:31], v[94:97], v[68:71], v[16:31]
	v_add_f32_e32 v72, v72, v73
	v_add_f32_e32 v74, v80, v72
	ds_bpermute_b32 v75, v168, v74
	v_lshl_add_u64 v[72:73], s[6:7], 0, v[150:151]
	v_lshl_add_u64 v[72:73], v[72:73], 0, s[8:9]
	s_waitcnt lgkmcnt(0)
	v_add_f32_e32 v74, v74, v75
	v_div_scale_f32 v75, s[26:27], v74, v74, 1.0
	v_rcp_f32_e32 v76, v75
	v_mfma_f32_32x32x16_bf16 v[0:15], v[64:67], v[68:71], v[0:15]
	v_fma_f32 v64, -v75, v76, 1.0
	v_fmac_f32_e32 v76, v64, v76
	v_div_scale_f32 v64, vcc, 1.0, v74, 1.0
	v_mul_f32_e32 v65, v64, v76
	v_fma_f32 v66, -v75, v65, v64
	v_fmac_f32_e32 v65, v66, v76
	v_fma_f32 v64, -v75, v65, v64
	v_div_fmas_f32 v64, v64, v76, v65
	v_div_fixup_f32 v64, v64, v74, 1.0
	v_pk_mul_f32 v[48:49], v[48:49], v[64:65] op_sel_hi:[1,0]
	v_pk_mul_f32 v[50:51], v[50:51], v[64:65] op_sel_hi:[1,0]
	v_pk_mul_f32 v[32:33], v[32:33], v[64:65] op_sel_hi:[1,0]
	v_pk_mul_f32 v[34:35], v[34:35], v[64:65] op_sel_hi:[1,0]
	v_pk_mul_f32 v[16:17], v[16:17], v[64:65] op_sel_hi:[1,0]
	v_pk_mul_f32 v[18:19], v[18:19], v[64:65] op_sel_hi:[1,0]
	v_pk_mul_f32 v[0:1], v[0:1], v[64:65] op_sel_hi:[1,0]
	v_pk_mul_f32 v[2:3], v[2:3], v[64:65] op_sel_hi:[1,0]
	v_pk_mul_f32 v[52:53], v[52:53], v[64:65] op_sel_hi:[1,0]
	v_pk_mul_f32 v[54:55], v[54:55], v[64:65] op_sel_hi:[1,0]
	v_pk_mul_f32 v[56:57], v[56:57], v[64:65] op_sel_hi:[1,0]
	v_pk_mul_f32 v[58:59], v[58:59], v[64:65] op_sel_hi:[1,0]
	v_pk_mul_f32 v[60:61], v[60:61], v[64:65] op_sel_hi:[1,0]
	v_pk_mul_f32 v[62:63], v[62:63], v[64:65] op_sel_hi:[1,0]
	v_pk_mul_f32 v[36:37], v[36:37], v[64:65] op_sel_hi:[1,0]
	v_pk_mul_f32 v[38:39], v[38:39], v[64:65] op_sel_hi:[1,0]
	v_pk_mul_f32 v[40:41], v[40:41], v[64:65] op_sel_hi:[1,0]
	v_pk_mul_f32 v[42:43], v[42:43], v[64:65] op_sel_hi:[1,0]
	v_pk_mul_f32 v[44:45], v[44:45], v[64:65] op_sel_hi:[1,0]
	v_pk_mul_f32 v[46:47], v[46:47], v[64:65] op_sel_hi:[1,0]
	v_pk_mul_f32 v[20:21], v[20:21], v[64:65] op_sel_hi:[1,0]
	v_pk_mul_f32 v[22:23], v[22:23], v[64:65] op_sel_hi:[1,0]
	v_pk_mul_f32 v[24:25], v[24:25], v[64:65] op_sel_hi:[1,0]
	v_pk_mul_f32 v[26:27], v[26:27], v[64:65] op_sel_hi:[1,0]
	v_pk_mul_f32 v[28:29], v[28:29], v[64:65] op_sel_hi:[1,0]
	v_pk_mul_f32 v[30:31], v[30:31], v[64:65] op_sel_hi:[1,0]
	v_pk_mul_f32 v[4:5], v[4:5], v[64:65] op_sel_hi:[1,0]
	v_pk_mul_f32 v[6:7], v[6:7], v[64:65] op_sel_hi:[1,0]
	v_pk_mul_f32 v[8:9], v[8:9], v[64:65] op_sel_hi:[1,0]
	v_pk_mul_f32 v[10:11], v[10:11], v[64:65] op_sel_hi:[1,0]
	v_pk_mul_f32 v[12:13], v[12:13], v[64:65] op_sel_hi:[1,0]
	v_pk_mul_f32 v[14:15], v[14:15], v[64:65] op_sel_hi:[1,0]
	v_lshl_add_u64 v[64:65], v[72:73], 0, v[144:145]
	v_cvt_pk_bf16_f32 v48, v48, v49
	v_cvt_pk_bf16_f32 v49, v50, v51
	v_cvt_pk_bf16_f32 v32, v32, v33
	v_cvt_pk_bf16_f32 v33, v34, v35
	v_cvt_pk_bf16_f32 v16, v16, v17
	v_cvt_pk_bf16_f32 v17, v18, v19
	v_cvt_pk_bf16_f32 v0, v0, v1
	v_cvt_pk_bf16_f32 v1, v2, v3
	global_store_dwordx2 v[64:65], v[48:49], off sc1
	v_cvt_pk_bf16_f32 v48, v52, v53
	v_cvt_pk_bf16_f32 v49, v54, v55
	global_store_dwordx2 v[64:65], v[32:33], off offset:64 sc1
	v_cvt_pk_bf16_f32 v32, v36, v37
	v_cvt_pk_bf16_f32 v33, v38, v39
	global_store_dwordx2 v[64:65], v[16:17], off offset:128 sc1
	v_cvt_pk_bf16_f32 v16, v20, v21
	v_cvt_pk_bf16_f32 v17, v22, v23
	global_store_dwordx2 v[64:65], v[0:1], off offset:192 sc1
	v_cvt_pk_bf16_f32 v0, v4, v5
	v_cvt_pk_bf16_f32 v1, v6, v7
	global_store_dwordx2 v[64:65], v[48:49], off offset:16 sc1
	v_cvt_pk_bf16_f32 v48, v56, v57
	v_cvt_pk_bf16_f32 v49, v58, v59
	global_store_dwordx2 v[64:65], v[32:33], off offset:80 sc1
	v_cvt_pk_bf16_f32 v32, v40, v41
	v_cvt_pk_bf16_f32 v33, v42, v43
	global_store_dwordx2 v[64:65], v[16:17], off offset:144 sc1
	v_cvt_pk_bf16_f32 v16, v24, v25
	v_cvt_pk_bf16_f32 v17, v26, v27
	global_store_dwordx2 v[64:65], v[0:1], off offset:208 sc1
	v_cvt_pk_bf16_f32 v0, v8, v9
	v_cvt_pk_bf16_f32 v1, v10, v11
	global_store_dwordx2 v[64:65], v[48:49], off offset:32 sc1
	v_cvt_pk_bf16_f32 v48, v60, v61
	v_cvt_pk_bf16_f32 v49, v62, v63
	global_store_dwordx2 v[64:65], v[32:33], off offset:96 sc1
	v_cvt_pk_bf16_f32 v32, v44, v45
	v_cvt_pk_bf16_f32 v33, v46, v47
	global_store_dwordx2 v[64:65], v[16:17], off offset:160 sc1
	v_cvt_pk_bf16_f32 v16, v28, v29
	v_cvt_pk_bf16_f32 v17, v30, v31
	global_store_dwordx2 v[64:65], v[0:1], off offset:224 sc1
	v_cvt_pk_bf16_f32 v0, v12, v13
	v_cvt_pk_bf16_f32 v1, v14, v15
	global_store_dwordx2 v[64:65], v[48:49], off offset:48 sc1
	global_store_dwordx2 v[64:65], v[32:33], off offset:112 sc1
	global_store_dwordx2 v[64:65], v[16:17], off offset:176 sc1
	global_store_dwordx2 v[64:65], v[0:1], off offset:240 sc1
	s_cbranch_scc1 .LBB0_1306

.LBB0_1296:
	v_pk_fma_f32 v[64:65], v[64:65], s[18:19], v[152:153] op_sel_hi:[1,0,1] neg_lo:[0,0,1] neg_hi:[0,0,1]
	v_pk_fma_f32 v[72:73], v[72:73], s[18:19], v[152:153] op_sel_hi:[1,0,1] neg_lo:[0,0,1] neg_hi:[0,0,1]
	v_exp_f32_e32 v190, v64
	v_exp_f32_e32 v191, v65
	v_pk_fma_f32 v[64:65], v[66:67], s[18:19], v[152:153] op_sel_hi:[1,0,1] neg_lo:[0,0,1] neg_hi:[0,0,1]
	ds_read_b128 v[174:177], v171 offset:17504
	v_exp_f32_e32 v192, v64
	v_exp_f32_e32 v193, v65
	v_pk_fma_f32 v[64:65], v[68:69], s[18:19], v[152:153] op_sel_hi:[1,0,1] neg_lo:[0,0,1] neg_hi:[0,0,1]
	v_pk_fma_f32 v[68:69], v[70:71], s[18:19], v[152:153] op_sel_hi:[1,0,1] neg_lo:[0,0,1] neg_hi:[0,0,1]
	v_exp_f32_e32 v194, v64
	v_exp_f32_e32 v195, v65
	ds_read_b128 v[64:67], v171 offset:17472
	v_exp_f32_e32 v196, v68
	v_exp_f32_e32 v197, v69
	v_cvt_pk_bf16_f32 v68, v190, v191
	v_cvt_pk_bf16_f32 v69, v192, v193
	v_cvt_pk_bf16_f32 v70, v194, v195
	v_cvt_pk_bf16_f32 v71, v196, v197
	v_exp_f32_e32 v72, v72
	v_exp_f32_e32 v73, v73
	s_waitcnt lgkmcnt(0)
	v_mfma_f32_32x32x16_bf16 v[48:63], v[64:67], v[68:71], v[48:63]
	ds_read_b128 v[64:67], v171 offset:22080
	ds_read_b128 v[178:181], v171 offset:22112
	s_add_i32 s25, s25, -1
	v_lshl_add_u64 v[154:155], v[154:155], 0, s[20:21]
	v_lshl_add_u64 v[156:157], v[156:157], 0, s[20:21]
	v_lshl_add_u64 v[158:159], v[158:159], 0, s[20:21]
	v_lshl_add_u64 v[160:161], v[160:161], 0, s[20:21]
	s_cmp_eq_u32 s25, 0
	s_waitcnt lgkmcnt(1)
	v_mfma_f32_32x32x16_bf16 v[32:47], v[64:67], v[68:71], v[32:47]
	ds_read_b128 v[64:67], v171 offset:26688
	ds_read_b128 v[182:185], v171 offset:31296
	ds_read_b128 v[186:189], v171 offset:26720
	v_lshl_add_u64 v[162:163], v[162:163], 0, s[22:23]
	s_waitcnt lgkmcnt(2)
	v_mfma_f32_32x32x16_bf16 v[16:31], v[64:67], v[68:71], v[16:31]
	v_fma_f32 v64, v74, s18, -v152
	v_fma_f32 v65, v75, s18, -v153
	v_exp_f32_e32 v74, v64
	v_exp_f32_e32 v75, v65
	v_pk_fma_f32 v[64:65], v[76:77], s[18:19], v[152:153] op_sel_hi:[1,0,1] neg_lo:[0,0,1] neg_hi:[0,0,1]
	s_nop 0
	v_exp_f32_e32 v76, v64
	v_exp_f32_e32 v77, v65
	ds_read_b128 v[64:67], v171 offset:31328
	s_waitcnt lgkmcnt(2)
	v_mfma_f32_32x32x16_bf16 v[0:15], v[182:185], v[68:71], v[0:15]
	v_fma_f32 v68, v78, s18, -v152
	v_fma_f32 v69, v79, s18, -v153
	v_cvt_pk_bf16_f32 v70, v76, v77
	v_exp_f32_e32 v78, v68
	v_exp_f32_e32 v79, v69
	v_cvt_pk_bf16_f32 v68, v72, v73
	v_cvt_pk_bf16_f32 v69, v74, v75
	v_cvt_pk_bf16_f32 v71, v78, v79
	s_nop 1
	v_mfma_f32_32x32x16_bf16 v[48:63], v[174:177], v[68:71], v[48:63]
	v_add_f32_e64 v174, v192, v190
	v_add_f32_e64 v175, v193, v191
	v_add_f32_e64 v174, v194, v174
	v_add_f32_e64 v175, v195, v175
	v_pk_add_f32 v[174:175], v[196:197], v[174:175]
	v_mfma_f32_32x32x16_bf16 v[32:47], v[178:181], v[68:71], v[32:47]
	v_add_f32_e64 v72, v72, v174
	v_add_f32_e64 v73, v73, v175
	v_add_f32_e64 v72, v74, v72
	v_add_f32_e64 v73, v75, v73
	v_add_f32_e64 v72, v76, v72
	v_add_f32_e64 v73, v77, v73
	v_pk_add_f32 v[72:73], v[78:79], v[72:73]
	s_waitcnt lgkmcnt(1)
	v_mfma_f32_32x32x16_bf16 v[16:31], v[186:189], v[68:71], v[16:31]
	v_add_f32_e32 v72, v72, v73
	v_add_f32_e32 v172, v172, v72
	s_waitcnt lgkmcnt(0)
	v_mfma_f32_32x32x16_bf16 v[0:15], v[64:67], v[68:71], v[0:15]
	s_cbranch_scc1 .LBB0_1301
.LBB0_1297:
	s_barrier
	s_waitcnt vmcnt(3)
	ds_write_b128 v166, v[112:115]
	s_waitcnt vmcnt(2)
	ds_write_b128 v166, v[116:119] offset:4352
	s_waitcnt vmcnt(1)
	ds_write_b128 v166, v[120:123] offset:8704
	s_waitcnt vmcnt(0)
	ds_write_b128 v166, v[124:127] offset:13056
	s_waitcnt vmcnt(1)
	ds_write_b128 v167, v[140:143] offset:17408
	ds_write_b128 v167, v[132:135] offset:22016
	ds_write_b128 v167, v[128:131] offset:26624
	s_waitcnt vmcnt(0)
	ds_write_b128 v167, v[136:139] offset:31232
	s_waitcnt lgkmcnt(0)
	s_barrier
	ds_read_b128 v[64:67], v170
	ds_read_b128 v[112:115], v170 offset:32
	s_waitcnt lgkmcnt(1)
	v_mfma_f32_32x32x16_bf16 v[64:79], v[64:67], v[108:111], 0
	v_lshl_add_u64 v[124:125], s[14:15], 0, v[162:163]
	v_add_co_u32_e32 v178, vcc, s37, v124
	v_lshl_add_u64 v[126:127], s[14:15], 0, v[154:155]
	s_nop 0
	v_addc_co_u32_e32 v179, vcc, 0, v125, vcc
	v_add_co_u32_e32 v180, vcc, s38, v124
	s_waitcnt lgkmcnt(0)
	v_mfma_f32_32x32x16_bf16 v[64:79], v[112:115], v[104:107], v[64:79]
	ds_read_b128 v[112:115], v170 offset:64
	ds_read_b128 v[116:119], v170 offset:96
	v_lshl_add_u64 v[128:129], s[14:15], 0, v[156:157]
	v_lshl_add_u64 v[130:131], s[14:15], 0, v[158:159]
	v_lshl_add_u64 v[136:137], s[14:15], 0, v[160:161]
	v_addc_co_u32_e32 v181, vcc, 0, v125, vcc
	v_add_co_u32_e32 v182, vcc, s39, v124
	s_waitcnt lgkmcnt(1)
	v_mfma_f32_32x32x16_bf16 v[64:79], v[112:115], v[100:103], v[64:79]
	ds_read_b128 v[112:115], v170 offset:128
	v_addc_co_u32_e32 v183, vcc, 0, v125, vcc
	v_add_co_u32_e32 v124, vcc, s40, v124
	s_nop 1
	v_addc_co_u32_e32 v125, vcc, 0, v125, vcc
	s_waitcnt lgkmcnt(1)
	v_mfma_f32_32x32x16_bf16 v[64:79], v[116:119], v[96:99], v[64:79]
	ds_read_b128 v[116:119], v170 offset:160
	ds_read_b128 v[120:123], v170 offset:192
	ds_read_b128 v[174:177], v170 offset:224
	s_waitcnt lgkmcnt(3)
	v_mfma_f32_32x32x16_bf16 v[64:79], v[112:115], v[92:95], v[64:79]
	s_waitcnt lgkmcnt(2)
	v_mfma_f32_32x32x16_bf16 v[64:79], v[116:119], v[88:91], v[64:79]
	global_load_dwordx4 v[140:143], v[126:127], off
	global_load_dwordx4 v[132:135], v[128:129], off
	s_nop 0
	global_load_dwordx4 v[128:131], v[130:131], off
	s_nop 0
	global_load_dwordx4 v[136:139], v[136:137], off
	s_nop 0
	global_load_dwordx4 v[112:115], v[178:179], off
	global_load_dwordx4 v[116:119], v[180:181], off
	s_waitcnt lgkmcnt(1)
	v_mfma_f32_32x32x16_bf16 v[64:79], v[120:123], v[84:87], v[64:79]
	global_load_dwordx4 v[120:123], v[182:183], off
	s_nop 0
	global_load_dwordx4 v[124:127], v[124:125], off
	s_waitcnt lgkmcnt(0)
	v_mfma_f32_32x32x16_bf16 v[64:79], v[174:177], v[80:83], v[64:79]
	s_nop 11
	v_max_f32_e32 v152, v64, v65
	v_max3_f32 v152, v152, v66, v67
	v_max3_f32 v152, v152, v68, v69
	v_max3_f32 v152, v152, v70, v71
	v_max3_f32 v152, v152, v72, v73
	v_max3_f32 v152, v152, v74, v75
	v_max3_f32 v152, v152, v76, v77
	v_max3_f32 v152, v152, v78, v79
	v_mov_b32_e32 v173, v152
	s_nop 1
	v_permlane32_swap_b32_e32 v173, v152
	s_waitcnt lgkmcnt(0)
	v_max_f32_e32 v152, v152, v173
	v_mul_f32_e32 v152, 0x3e0293ee, v152
	v_add_f32_e32 v250, 0xc1000000, v152
	v_cmp_gt_f32_e32 vcc, v250, v153
	s_cbranch_vccz .LBB0_1299
	v_max_f32_e32 v152, v152, v152
	v_max_f32_e32 v173, v153, v153
	v_max_f32_e32 v173, v173, v152
	v_sub_f32_e32 v152, v153, v173
	v_exp_f32_e32 v152, v152
	s_nop 0
	v_pk_mul_f32 v[62:63], v[62:63], v[152:153] op_sel_hi:[1,0]
	v_pk_mul_f32 v[60:61], v[60:61], v[152:153] op_sel_hi:[1,0]
	v_pk_mul_f32 v[58:59], v[58:59], v[152:153] op_sel_hi:[1,0]
	v_pk_mul_f32 v[56:57], v[56:57], v[152:153] op_sel_hi:[1,0]
	v_pk_mul_f32 v[54:55], v[54:55], v[152:153] op_sel_hi:[1,0]
	v_pk_mul_f32 v[52:53], v[52:53], v[152:153] op_sel_hi:[1,0]
	v_pk_mul_f32 v[50:51], v[50:51], v[152:153] op_sel_hi:[1,0]
	v_pk_mul_f32 v[48:49], v[48:49], v[152:153] op_sel_hi:[1,0]
	v_pk_mul_f32 v[46:47], v[46:47], v[152:153] op_sel_hi:[1,0]
	v_pk_mul_f32 v[44:45], v[44:45], v[152:153] op_sel_hi:[1,0]
	v_pk_mul_f32 v[42:43], v[42:43], v[152:153] op_sel_hi:[1,0]
	v_pk_mul_f32 v[40:41], v[40:41], v[152:153] op_sel_hi:[1,0]
	v_pk_mul_f32 v[38:39], v[38:39], v[152:153] op_sel_hi:[1,0]
	v_pk_mul_f32 v[36:37], v[36:37], v[152:153] op_sel_hi:[1,0]
	v_pk_mul_f32 v[34:35], v[34:35], v[152:153] op_sel_hi:[1,0]
	v_pk_mul_f32 v[32:33], v[32:33], v[152:153] op_sel_hi:[1,0]
	v_pk_mul_f32 v[30:31], v[30:31], v[152:153] op_sel_hi:[1,0]
	v_pk_mul_f32 v[28:29], v[28:29], v[152:153] op_sel_hi:[1,0]
	v_pk_mul_f32 v[26:27], v[26:27], v[152:153] op_sel_hi:[1,0]
	v_pk_mul_f32 v[24:25], v[24:25], v[152:153] op_sel_hi:[1,0]
	v_pk_mul_f32 v[22:23], v[22:23], v[152:153] op_sel_hi:[1,0]
	v_pk_mul_f32 v[20:21], v[20:21], v[152:153] op_sel_hi:[1,0]
	v_pk_mul_f32 v[18:19], v[18:19], v[152:153] op_sel_hi:[1,0]
	v_pk_mul_f32 v[16:17], v[16:17], v[152:153] op_sel_hi:[1,0]
	v_pk_mul_f32 v[14:15], v[14:15], v[152:153] op_sel_hi:[1,0]
	v_pk_mul_f32 v[12:13], v[12:13], v[152:153] op_sel_hi:[1,0]
	v_pk_mul_f32 v[10:11], v[10:11], v[152:153] op_sel_hi:[1,0]
	v_pk_mul_f32 v[8:9], v[8:9], v[152:153] op_sel_hi:[1,0]
	v_pk_mul_f32 v[6:7], v[6:7], v[152:153] op_sel_hi:[1,0]
	v_pk_mul_f32 v[4:5], v[4:5], v[152:153] op_sel_hi:[1,0]
	v_pk_mul_f32 v[2:3], v[2:3], v[152:153] op_sel_hi:[1,0]
	v_pk_mul_f32 v[0:1], v[0:1], v[152:153] op_sel_hi:[1,0]
	v_mul_f32_e32 v172, v172, v152
	v_mov_b32_e32 v153, v173
.LBB0_1299:
	v_mov_b32_e32 v152, v153
	v_pk_fma_f32 v[64:65], v[64:65], s[18:19], v[152:153] op_sel_hi:[1,0,0] neg_lo:[0,0,1] neg_hi:[0,0,1]
	v_pk_fma_f32 v[72:73], v[72:73], s[18:19], v[152:153] op_sel_hi:[1,0,0] neg_lo:[0,0,1] neg_hi:[0,0,1]
	v_exp_f32_e32 v202, v64
	v_exp_f32_e32 v203, v65
	v_pk_fma_f32 v[64:65], v[66:67], s[18:19], v[152:153] op_sel_hi:[1,0,0] neg_lo:[0,0,1] neg_hi:[0,0,1]
	ds_read_b128 v[174:177], v171 offset:17440
	v_exp_f32_e32 v204, v64
	v_exp_f32_e32 v205, v65
	v_pk_fma_f32 v[64:65], v[68:69], s[18:19], v[152:153] op_sel_hi:[1,0,0] neg_lo:[0,0,1] neg_hi:[0,0,1]
	v_pk_fma_f32 v[68:69], v[70:71], s[18:19], v[152:153] op_sel_hi:[1,0,0] neg_lo:[0,0,1] neg_hi:[0,0,1]
	v_exp_f32_e32 v206, v64
	v_exp_f32_e32 v207, v65
	ds_read_b128 v[64:67], v171 offset:17408
	v_exp_f32_e32 v208, v68
	v_exp_f32_e32 v209, v69
	v_cvt_pk_bf16_f32 v68, v202, v203
	v_cvt_pk_bf16_f32 v69, v204, v205
	v_cvt_pk_bf16_f32 v70, v206, v207
	v_cvt_pk_bf16_f32 v71, v208, v209
	v_exp_f32_e32 v210, v72
	v_exp_f32_e32 v211, v73
	s_waitcnt lgkmcnt(0)
	v_mfma_f32_32x32x16_bf16 v[48:63], v[64:67], v[68:71], v[48:63]
	ds_read_b128 v[64:67], v171 offset:22016
	ds_read_b128 v[178:181], v171 offset:22048
	s_waitcnt lgkmcnt(1)
	v_mfma_f32_32x32x16_bf16 v[32:47], v[64:67], v[68:71], v[32:47]
	ds_read_b128 v[64:67], v171 offset:26624
	ds_read_b128 v[182:185], v171 offset:31232
	ds_read_b128 v[186:189], v171 offset:26656
	ds_read_b128 v[190:193], v171 offset:31264
	s_waitcnt lgkmcnt(3)
	v_mfma_f32_32x32x16_bf16 v[16:31], v[64:67], v[68:71], v[16:31]
	v_fma_f32 v64, v74, s18, -v152
	v_fma_f32 v65, v75, s18, -v152
	v_exp_f32_e32 v212, v64
	v_exp_f32_e32 v213, v65
	v_pk_fma_f32 v[64:65], v[76:77], s[18:19], v[152:153] op_sel_hi:[1,0,0] neg_lo:[0,0,1] neg_hi:[0,0,1]
	s_nop 0
	v_exp_f32_e32 v214, v64
	v_exp_f32_e32 v215, v65
	v_pk_fma_f32 v[64:65], v[78:79], s[18:19], v[152:153] op_sel_hi:[1,0,0] neg_lo:[0,0,1] neg_hi:[0,0,1]
	s_waitcnt lgkmcnt(2)
	v_mfma_f32_32x32x16_bf16 v[0:15], v[182:185], v[68:71], v[0:15]
	v_exp_f32_e32 v216, v64
	v_exp_f32_e32 v217, v65
	v_cvt_pk_bf16_f32 v182, v210, v211
	v_cvt_pk_bf16_f32 v183, v212, v213
	v_cvt_pk_bf16_f32 v184, v214, v215
	v_cvt_pk_bf16_f32 v185, v216, v217
	s_nop 1
	v_mfma_f32_32x32x16_bf16 v[48:63], v[174:177], v[182:185], v[48:63]
	ds_read_b128 v[64:67], v170 offset:8704
	ds_read_b128 v[174:177], v170 offset:8736
	s_waitcnt lgkmcnt(1)
	v_mfma_f32_32x32x16_bf16 v[64:79], v[64:67], v[108:111], 0
	s_waitcnt lgkmcnt(0)
	v_mfma_f32_32x32x16_bf16 v[64:79], v[174:177], v[104:107], v[64:79]
	ds_read_b128 v[174:177], v170 offset:8768
	ds_read_b128 v[194:197], v170 offset:8800
	s_waitcnt lgkmcnt(1)
	v_mfma_f32_32x32x16_bf16 v[64:79], v[174:177], v[100:103], v[64:79]
	s_waitcnt lgkmcnt(0)
	v_mfma_f32_32x32x16_bf16 v[64:79], v[194:197], v[96:99], v[64:79]
	ds_read_b128 v[174:177], v170 offset:8832
	ds_read_b128 v[194:197], v170 offset:8864
	s_waitcnt lgkmcnt(1)
	v_mfma_f32_32x32x16_bf16 v[64:79], v[174:177], v[92:95], v[64:79]
	s_waitcnt lgkmcnt(0)
	v_mfma_f32_32x32x16_bf16 v[64:79], v[194:197], v[88:91], v[64:79]
	ds_read_b128 v[174:177], v170 offset:8896
	ds_read_b128 v[194:197], v170 offset:8928
	s_waitcnt lgkmcnt(1)
	v_mfma_f32_32x32x16_bf16 v[64:79], v[174:177], v[84:87], v[64:79]
	v_add_f32_e64 v174, v204, v202
	v_add_f32_e64 v175, v205, v203
	v_add_f32_e64 v174, v206, v174
	v_add_f32_e64 v175, v207, v175
	v_pk_add_f32 v[174:175], v[208:209], v[174:175]
	s_waitcnt lgkmcnt(0)
	v_mfma_f32_32x32x16_bf16 v[64:79], v[194:197], v[80:83], v[64:79]
	v_add_f32_e64 v174, v210, v174
	v_add_f32_e64 v175, v211, v175
	v_add_f32_e64 v174, v212, v174
	v_add_f32_e64 v175, v213, v175
	v_add_f32_e64 v174, v214, v174
	v_add_f32_e64 v175, v215, v175
	s_nop 5
	v_max_f32_e32 v152, v64, v65
	v_max3_f32 v152, v152, v66, v67
	v_max3_f32 v152, v152, v68, v69
	v_max3_f32 v152, v152, v70, v71
	v_max3_f32 v152, v152, v72, v73
	v_max3_f32 v152, v152, v74, v75
	v_max3_f32 v152, v152, v76, v77
	v_max3_f32 v152, v152, v78, v79
	v_mov_b32_e32 v173, v152
	s_nop 1
	v_permlane32_swap_b32_e32 v173, v152
	v_mfma_f32_32x32x16_bf16 v[32:47], v[178:181], v[182:185], v[32:47]
	v_add_f32_e64 v174, v216, v174
	v_add_f32_e64 v175, v217, v175
	s_waitcnt lgkmcnt(0)
	v_max_f32_e32 v173, v173, v173
	v_max_f32_e32 v152, v152, v173
	v_add_f32_e32 v174, v174, v175
	v_mul_f32_e32 v152, 0x3e0293ee, v152
	v_mfma_f32_32x32x16_bf16 v[16:31], v[186:189], v[182:185], v[16:31]
	v_add_f32_e32 v172, v172, v174
	v_add_f32_e32 v250, 0xc1000000, v152
	v_cmp_gt_f32_e32 vcc, v250, v153
	v_mfma_f32_32x32x16_bf16 v[0:15], v[190:193], v[182:185], v[0:15]
	s_cbranch_vccnz .LBB0_1295
	v_mov_b32_e32 v152, v153
	s_branch .LBB0_1296
.LBB0_1301:
	s_barrier
	s_waitcnt vmcnt(3)
	ds_write_b128 v166, v[112:115]
	s_waitcnt vmcnt(2)
	ds_write_b128 v166, v[116:119] offset:4352
	s_waitcnt vmcnt(1)
	ds_write_b128 v166, v[120:123] offset:8704
	s_waitcnt vmcnt(0)
	ds_write_b128 v166, v[124:127] offset:13056
	ds_write_b128 v167, v[140:143] offset:17408
	ds_write_b128 v167, v[132:135] offset:22016
	ds_write_b128 v167, v[128:131] offset:26624
	ds_write_b128 v167, v[136:139] offset:31232
	s_waitcnt lgkmcnt(0)
	s_barrier
	ds_read_b128 v[64:67], v170
	ds_read_b128 v[112:115], v170 offset:32
	s_waitcnt lgkmcnt(1)
	v_mfma_f32_32x32x16_bf16 v[64:79], v[64:67], v[108:111], 0
	s_waitcnt lgkmcnt(0)
	v_mfma_f32_32x32x16_bf16 v[64:79], v[112:115], v[104:107], v[64:79]
	ds_read_b128 v[112:115], v170 offset:64
	ds_read_b128 v[116:119], v170 offset:96
	s_waitcnt lgkmcnt(1)
	v_mfma_f32_32x32x16_bf16 v[64:79], v[112:115], v[100:103], v[64:79]
	s_waitcnt lgkmcnt(0)
	v_mfma_f32_32x32x16_bf16 v[64:79], v[116:119], v[96:99], v[64:79]
	ds_read_b128 v[112:115], v170 offset:128
	ds_read_b128 v[116:119], v170 offset:160
	s_waitcnt lgkmcnt(1)
	v_mfma_f32_32x32x16_bf16 v[64:79], v[112:115], v[92:95], v[64:79]
	s_waitcnt lgkmcnt(0)
	v_mfma_f32_32x32x16_bf16 v[64:79], v[116:119], v[88:91], v[64:79]
	ds_read_b128 v[112:115], v170 offset:192
	ds_read_b128 v[116:119], v170 offset:224
	s_waitcnt lgkmcnt(1)
	v_mfma_f32_32x32x16_bf16 v[64:79], v[112:115], v[84:87], v[64:79]
	s_waitcnt lgkmcnt(0)
	v_mfma_f32_32x32x16_bf16 v[64:79], v[116:119], v[80:83], v[64:79]
	s_nop 11
	v_max_f32_e32 v112, v64, v65
	v_max3_f32 v112, v112, v66, v67
	v_max3_f32 v112, v112, v68, v69
	v_max3_f32 v112, v112, v70, v71
	v_max3_f32 v112, v112, v72, v73
	v_max3_f32 v112, v112, v74, v75
	v_max3_f32 v112, v112, v76, v77
	v_max3_f32 v112, v112, v78, v79
	v_mov_b32_e32 v113, v112
	s_nop 1
	v_permlane32_swap_b32_e32 v113, v112
	s_waitcnt lgkmcnt(0)
	v_max_f32_e32 v112, v112, v113
	v_mul_f32_e32 v112, 0x3e0293ee, v112
	v_add_f32_e32 v250, 0xc1000000, v112
	v_cmp_gt_f32_e32 vcc, v250, v153
	s_cbranch_vccz .LBB0_1303
	v_max_f32_e32 v112, v112, v112
	v_max_f32_e32 v113, v153, v153
	v_max_f32_e32 v152, v113, v112
	v_sub_f32_e32 v112, v153, v152
	v_exp_f32_e32 v112, v112
	v_mov_b32_e32 v153, v152
	v_pk_mul_f32 v[62:63], v[62:63], v[112:113] op_sel_hi:[1,0]
	v_pk_mul_f32 v[60:61], v[60:61], v[112:113] op_sel_hi:[1,0]
	v_pk_mul_f32 v[58:59], v[58:59], v[112:113] op_sel_hi:[1,0]
	v_pk_mul_f32 v[56:57], v[56:57], v[112:113] op_sel_hi:[1,0]
	v_pk_mul_f32 v[54:55], v[54:55], v[112:113] op_sel_hi:[1,0]
	v_pk_mul_f32 v[52:53], v[52:53], v[112:113] op_sel_hi:[1,0]
	v_pk_mul_f32 v[50:51], v[50:51], v[112:113] op_sel_hi:[1,0]
	v_pk_mul_f32 v[48:49], v[48:49], v[112:113] op_sel_hi:[1,0]
	v_pk_mul_f32 v[46:47], v[46:47], v[112:113] op_sel_hi:[1,0]
	v_pk_mul_f32 v[44:45], v[44:45], v[112:113] op_sel_hi:[1,0]
	v_pk_mul_f32 v[42:43], v[42:43], v[112:113] op_sel_hi:[1,0]
	v_pk_mul_f32 v[40:41], v[40:41], v[112:113] op_sel_hi:[1,0]
	v_pk_mul_f32 v[38:39], v[38:39], v[112:113] op_sel_hi:[1,0]
	v_pk_mul_f32 v[36:37], v[36:37], v[112:113] op_sel_hi:[1,0]
	v_pk_mul_f32 v[34:35], v[34:35], v[112:113] op_sel_hi:[1,0]
	v_pk_mul_f32 v[32:33], v[32:33], v[112:113] op_sel_hi:[1,0]
	v_pk_mul_f32 v[30:31], v[30:31], v[112:113] op_sel_hi:[1,0]
	v_pk_mul_f32 v[28:29], v[28:29], v[112:113] op_sel_hi:[1,0]
	v_pk_mul_f32 v[26:27], v[26:27], v[112:113] op_sel_hi:[1,0]
	v_pk_mul_f32 v[24:25], v[24:25], v[112:113] op_sel_hi:[1,0]
	v_pk_mul_f32 v[22:23], v[22:23], v[112:113] op_sel_hi:[1,0]
	v_pk_mul_f32 v[20:21], v[20:21], v[112:113] op_sel_hi:[1,0]
	v_pk_mul_f32 v[18:19], v[18:19], v[112:113] op_sel_hi:[1,0]
	v_pk_mul_f32 v[16:17], v[16:17], v[112:113] op_sel_hi:[1,0]
	v_pk_mul_f32 v[14:15], v[14:15], v[112:113] op_sel_hi:[1,0]
	v_pk_mul_f32 v[12:13], v[12:13], v[112:113] op_sel_hi:[1,0]
	v_pk_mul_f32 v[10:11], v[10:11], v[112:113] op_sel_hi:[1,0]
	v_pk_mul_f32 v[8:9], v[8:9], v[112:113] op_sel_hi:[1,0]
	v_pk_mul_f32 v[6:7], v[6:7], v[112:113] op_sel_hi:[1,0]
	v_pk_mul_f32 v[4:5], v[4:5], v[112:113] op_sel_hi:[1,0]
	v_pk_mul_f32 v[2:3], v[2:3], v[112:113] op_sel_hi:[1,0]
	v_pk_mul_f32 v[0:1], v[0:1], v[112:113] op_sel_hi:[1,0]
	v_mul_f32_e32 v172, v172, v112
	v_mov_b32_e32 v112, v152
	s_branch .LBB0_1304

.LBB0_1304:
	v_pk_fma_f32 v[64:65], v[64:65], s[18:19], v[152:153] op_sel_hi:[1,0,1] neg_lo:[0,0,1] neg_hi:[0,0,1]
	v_pk_fma_f32 v[72:73], v[72:73], s[18:19], v[152:153] op_sel_hi:[1,0,1] neg_lo:[0,0,1] neg_hi:[0,0,1]
	v_exp_f32_e32 v134, v64
	v_exp_f32_e32 v135, v65
	v_pk_fma_f32 v[64:65], v[66:67], s[18:19], v[152:153] op_sel_hi:[1,0,1] neg_lo:[0,0,1] neg_hi:[0,0,1]
	ds_read_b128 v[114:117], v171 offset:17440
	v_exp_f32_e32 v136, v64
	v_exp_f32_e32 v137, v65
	v_pk_fma_f32 v[64:65], v[68:69], s[18:19], v[152:153] op_sel_hi:[1,0,1] neg_lo:[0,0,1] neg_hi:[0,0,1]
	v_pk_fma_f32 v[68:69], v[70:71], s[18:19], v[152:153] op_sel_hi:[1,0,1] neg_lo:[0,0,1] neg_hi:[0,0,1]
	v_exp_f32_e32 v138, v64
	v_exp_f32_e32 v139, v65
	ds_read_b128 v[64:67], v171 offset:17408
	v_exp_f32_e32 v140, v68
	v_exp_f32_e32 v141, v69
	v_cvt_pk_bf16_f32 v68, v134, v135
	v_cvt_pk_bf16_f32 v69, v136, v137
	v_cvt_pk_bf16_f32 v70, v138, v139
	v_cvt_pk_bf16_f32 v71, v140, v141
	v_exp_f32_e32 v142, v72
	v_exp_f32_e32 v143, v73
	s_waitcnt lgkmcnt(0)
	v_mfma_f32_32x32x16_bf16 v[48:63], v[64:67], v[68:71], v[48:63]
	ds_read_b128 v[64:67], v171 offset:22016
	ds_read_b128 v[118:121], v171 offset:22048
	s_waitcnt lgkmcnt(1)
	v_mfma_f32_32x32x16_bf16 v[32:47], v[64:67], v[68:71], v[32:47]
	ds_read_b128 v[64:67], v171 offset:26624
	ds_read_b128 v[122:125], v171 offset:31232
	ds_read_b128 v[126:129], v171 offset:26656
	ds_read_b128 v[130:133], v171 offset:31264
	s_waitcnt lgkmcnt(3)
	v_mfma_f32_32x32x16_bf16 v[16:31], v[64:67], v[68:71], v[16:31]
	v_fma_f32 v64, v74, s18, -v152
	v_fma_f32 v65, v75, s18, -v153
	v_exp_f32_e32 v154, v64
	v_exp_f32_e32 v155, v65
	v_pk_fma_f32 v[64:65], v[76:77], s[18:19], v[152:153] op_sel_hi:[1,0,1] neg_lo:[0,0,1] neg_hi:[0,0,1]
	s_nop 0
	v_exp_f32_e32 v156, v64
	v_exp_f32_e32 v157, v65
	v_pk_fma_f32 v[64:65], v[78:79], s[18:19], v[152:153] op_sel_hi:[1,0,1] neg_lo:[0,0,1] neg_hi:[0,0,1]
	s_waitcnt lgkmcnt(2)
	v_mfma_f32_32x32x16_bf16 v[0:15], v[122:125], v[68:71], v[0:15]
	v_exp_f32_e32 v158, v64
	v_exp_f32_e32 v159, v65
	v_cvt_pk_bf16_f32 v122, v142, v143
	v_cvt_pk_bf16_f32 v123, v154, v155
	v_cvt_pk_bf16_f32 v124, v156, v157
	v_cvt_pk_bf16_f32 v125, v158, v159
	s_nop 1
	v_mfma_f32_32x32x16_bf16 v[48:63], v[114:117], v[122:125], v[48:63]
	ds_read_b128 v[64:67], v170 offset:8704
	ds_read_b128 v[114:117], v170 offset:8736
	s_waitcnt lgkmcnt(1)
	v_mfma_f32_32x32x16_bf16 v[64:79], v[64:67], v[108:111], 0
	s_waitcnt lgkmcnt(0)
	v_mfma_f32_32x32x16_bf16 v[64:79], v[114:117], v[104:107], v[64:79]
	ds_read_b128 v[104:107], v170 offset:8768
	ds_read_b128 v[108:111], v170 offset:8800
	s_waitcnt lgkmcnt(1)
	v_mfma_f32_32x32x16_bf16 v[64:79], v[104:107], v[100:103], v[64:79]
	s_waitcnt lgkmcnt(0)
	v_mfma_f32_32x32x16_bf16 v[64:79], v[108:111], v[96:99], v[64:79]
	ds_read_b128 v[96:99], v170 offset:8832
	ds_read_b128 v[100:103], v170 offset:8864
	s_waitcnt lgkmcnt(1)
	v_mfma_f32_32x32x16_bf16 v[64:79], v[96:99], v[92:95], v[64:79]
	s_waitcnt lgkmcnt(0)
	v_mfma_f32_32x32x16_bf16 v[64:79], v[100:103], v[88:91], v[64:79]
	ds_read_b128 v[88:91], v170 offset:8896
	ds_read_b128 v[92:95], v170 offset:8928
	s_waitcnt lgkmcnt(1)
	v_mfma_f32_32x32x16_bf16 v[64:79], v[88:91], v[84:87], v[64:79]
	v_add_f32_e64 v84, v136, v134
	v_add_f32_e64 v85, v137, v135
	v_add_f32_e64 v84, v138, v84
	v_add_f32_e64 v85, v139, v85
	v_pk_add_f32 v[84:85], v[140:141], v[84:85]
	s_waitcnt lgkmcnt(0)
	v_mfma_f32_32x32x16_bf16 v[64:79], v[92:95], v[80:83], v[64:79]
	v_add_f32_e64 v80, v142, v84
	v_add_f32_e64 v81, v143, v85
	v_add_f32_e64 v80, v154, v80
	v_add_f32_e64 v81, v155, v81
	v_add_f32_e64 v80, v156, v80
	v_add_f32_e64 v81, v157, v81
	s_nop 5
	v_max_f32_e32 v82, v64, v65
	v_max3_f32 v82, v82, v66, v67
	v_max3_f32 v82, v82, v68, v69
	v_max3_f32 v82, v82, v70, v71
	v_max3_f32 v82, v82, v72, v73
	v_max3_f32 v82, v82, v74, v75
	v_max3_f32 v82, v82, v76, v77
	v_max3_f32 v82, v82, v78, v79
	ds_bpermute_b32 v83, v168, v82
	v_mfma_f32_32x32x16_bf16 v[32:47], v[118:121], v[122:125], v[32:47]
	v_add_f32_e64 v80, v158, v80
	v_add_f32_e64 v81, v159, v81
	v_add_f32_e32 v80, v80, v81
	s_waitcnt lgkmcnt(0)
	v_max_f32_e32 v81, v83, v83
	v_max_f32_e32 v81, v82, v81
	v_mul_f32_e32 v81, 0x3e0293ee, v81
	v_add_f32_e32 v80, v172, v80
	v_mfma_f32_32x32x16_bf16 v[16:31], v[126:129], v[122:125], v[16:31]
	v_add_f32_e32 v250, 0xc1000000, v81
	v_cmp_gt_f32_e32 vcc, v250, v112
	v_mfma_f32_32x32x16_bf16 v[0:15], v[130:133], v[122:125], v[0:15]
	s_cbranch_vccz .LBB0_1285
	v_max_f32_e32 v81, v81, v81
	v_max_f32_e32 v82, v112, v112
	v_max_f32_e32 v152, v82, v81
	v_sub_f32_e32 v81, v112, v152
	v_exp_f32_e32 v82, v81
	v_mov_b32_e32 v153, v152
	v_pk_mul_f32 v[62:63], v[62:63], v[82:83] op_sel_hi:[1,0]
	v_pk_mul_f32 v[60:61], v[60:61], v[82:83] op_sel_hi:[1,0]
	v_pk_mul_f32 v[58:59], v[58:59], v[82:83] op_sel_hi:[1,0]
	v_pk_mul_f32 v[56:57], v[56:57], v[82:83] op_sel_hi:[1,0]
	v_pk_mul_f32 v[54:55], v[54:55], v[82:83] op_sel_hi:[1,0]
	v_pk_mul_f32 v[52:53], v[52:53], v[82:83] op_sel_hi:[1,0]
	v_pk_mul_f32 v[50:51], v[50:51], v[82:83] op_sel_hi:[1,0]
	v_pk_mul_f32 v[48:49], v[48:49], v[82:83] op_sel_hi:[1,0]
	v_pk_mul_f32 v[46:47], v[46:47], v[82:83] op_sel_hi:[1,0]
	v_pk_mul_f32 v[44:45], v[44:45], v[82:83] op_sel_hi:[1,0]
	v_pk_mul_f32 v[42:43], v[42:43], v[82:83] op_sel_hi:[1,0]
	v_pk_mul_f32 v[40:41], v[40:41], v[82:83] op_sel_hi:[1,0]
	v_pk_mul_f32 v[38:39], v[38:39], v[82:83] op_sel_hi:[1,0]
	v_pk_mul_f32 v[36:37], v[36:37], v[82:83] op_sel_hi:[1,0]
	v_pk_mul_f32 v[34:35], v[34:35], v[82:83] op_sel_hi:[1,0]
	v_pk_mul_f32 v[32:33], v[32:33], v[82:83] op_sel_hi:[1,0]
	v_pk_mul_f32 v[30:31], v[30:31], v[82:83] op_sel_hi:[1,0]
	v_pk_mul_f32 v[28:29], v[28:29], v[82:83] op_sel_hi:[1,0]
	v_pk_mul_f32 v[26:27], v[26:27], v[82:83] op_sel_hi:[1,0]
	v_pk_mul_f32 v[24:25], v[24:25], v[82:83] op_sel_hi:[1,0]
	v_pk_mul_f32 v[22:23], v[22:23], v[82:83] op_sel_hi:[1,0]
	v_pk_mul_f32 v[20:21], v[20:21], v[82:83] op_sel_hi:[1,0]
	v_pk_mul_f32 v[18:19], v[18:19], v[82:83] op_sel_hi:[1,0]
	v_pk_mul_f32 v[16:17], v[16:17], v[82:83] op_sel_hi:[1,0]
	v_pk_mul_f32 v[14:15], v[14:15], v[82:83] op_sel_hi:[1,0]
	v_pk_mul_f32 v[12:13], v[12:13], v[82:83] op_sel_hi:[1,0]
	v_pk_mul_f32 v[10:11], v[10:11], v[82:83] op_sel_hi:[1,0]
	v_pk_mul_f32 v[8:9], v[8:9], v[82:83] op_sel_hi:[1,0]
	v_pk_mul_f32 v[6:7], v[6:7], v[82:83] op_sel_hi:[1,0]
	v_pk_mul_f32 v[4:5], v[4:5], v[82:83] op_sel_hi:[1,0]
	v_pk_mul_f32 v[2:3], v[2:3], v[82:83] op_sel_hi:[1,0]
	v_pk_mul_f32 v[0:1], v[0:1], v[82:83] op_sel_hi:[1,0]
	v_mul_f32_e32 v80, v80, v82
	s_branch .LBB0_1285
